# P11 epilogue: final loop loads batched four row groups deep, the first 20 (norm weights + x rows of four row groups) issued before the row-statistics exchange
# speedup vs baseline: 1.0017x; 1.0017x over previous
; #define PG8_LAS __attribute__((address_space(3)))
;     __device__ __forceinline__ void fused(f32x4 (&acc)[2][2][4][2], const Unit& u, int wr, int wc, int fr, int fq, PG8_LAS unsigned char* lds, int wid, int lane) const {
;     ...
;         asm volatile("s_waitcnt lgkmcnt(0)" ::: "memory"); __builtin_amdgcn_s_barrier(); asm volatile("" ::: "memory");
;         const int row = wid * 32 + (lane & 31);
;         if (lane < 32) { const f32x4 p = *(const PG8_LAS f32x4*)(P + row * 4);
;             __hip_atomic_store(xbuf + (size_t)(u.pm * BM + row) * 4 + u.pn, (p[0] + p[1]) + (p[2] + p[3]), __ATOMIC_RELAXED, __HIP_MEMORY_SCOPE_AGENT); }
;     ...
;         const int col0 = u.pn * BM + wc * 32 + 4 * fq;
; #pragma unroll
;         for (int ai = 0; ai < 2; ++ai)
; #pragma unroll
;             for (int m = 0; m < 4; ++m) { const int r = ai * HALF + wr * 64 + m * 16 + fr; const float rs = R[r]; const size_t off = (size_t)(u.pm * BM + r) * 1024 + col0;
; #pragma unroll
;                 for (int bj = 0; bj < 2; ++bj)
; #pragma unroll
;                     for (int n = 0; n < 2; ++n) { const int c = bj * HALF + n * 16; const f32x4 xv = *(const f32x4*)(xres + off + c); const f32x4 wv = *(const f32x4*)(w + col0 + c);
.LBB0_989:
	s_or_b64 exec, exec, s[0:1]
	v_readlane_b32 s8, v250, 0
	v_readlane_b32 s14, v250, 6
	s_waitcnt lgkmcnt(0)
	s_barrier
	v_readlane_b32 s98, v250, 10
	v_readlane_b32 s99, v250, 11
	v_readlane_b32 vcc_lo, v250, 2
	v_readlane_b32 vcc_hi, v250, 3
	s_lshl_b32 s16, s4, 8
	s_lshl_b32 s17, s34, 5
	s_lshl_b32 s18, s6, 8
	s_or_b32 s17, s18, s17
	v_lshrrev_b32_e32 v244, 2, v0
	v_add_u32_e32 v246, s16, v146
	v_and_or_b32 v244, v244, 12, s17
	v_ashrrev_i32_e32 v247, 31, v246
	v_ashrrev_i32_e32 v245, 31, v244
	v_lshlrev_b64 v[246:247], 10, v[246:247]
	v_lshl_add_u64 v[246:247], v[246:247], 0, v[244:245]
	v_lshlrev_b64 v[142:143], 2, v[246:247]
	v_lshlrev_b32_e32 v144, 2, v244
	v_mov_b32_e32 v228, v142
	v_add_u32_e32 v229, 0x10000, v142
	v_add_u32_e32 v230, 0x20000, v142
	v_add_u32_e32 v231, 0x30000, v142
	v_add_u32_e32 v232, 0x80000, v142
	v_add_u32_e32 v233, 0x90000, v142
	v_add_u32_e32 v234, 0xa0000, v142
	v_add_u32_e32 v235, 0xb0000, v142
	global_load_dwordx4 v[148:151], v144, vcc
	global_load_dwordx4 v[152:155], v144, vcc offset:64
	global_load_dwordx4 v[156:159], v144, vcc offset:512
	global_load_dwordx4 v[160:163], v144, vcc offset:576
	global_load_dwordx4 v[164:167], v228, s[98:99]
	global_load_dwordx4 v[168:171], v228, s[98:99] offset:64
	global_load_dwordx4 v[172:175], v228, s[98:99] offset:512
	global_load_dwordx4 v[176:179], v228, s[98:99] offset:576
	global_load_dwordx4 v[180:183], v229, s[98:99]
	global_load_dwordx4 v[184:187], v229, s[98:99] offset:64
	global_load_dwordx4 v[188:191], v229, s[98:99] offset:512
	global_load_dwordx4 v[192:195], v229, s[98:99] offset:576
	global_load_dwordx4 v[196:199], v230, s[98:99]
	global_load_dwordx4 v[200:203], v230, s[98:99] offset:64
	global_load_dwordx4 v[204:207], v230, s[98:99] offset:512
	global_load_dwordx4 v[208:211], v230, s[98:99] offset:576
	global_load_dwordx4 v[212:215], v231, s[98:99]
	global_load_dwordx4 v[216:219], v231, s[98:99] offset:64
	global_load_dwordx4 v[220:223], v231, s[98:99] offset:512
	global_load_dwordx4 v[224:227], v231, s[98:99] offset:576
	v_readlane_b32 s15, v250, 7
	s_add_u32 s2, s14, 0xfa70000
	s_waitcnt lgkmcnt(0)
	v_and_b32_e32 v1, 31, v0
	v_readlane_b32 s9, v250, 1
	s_addc_u32 s3, s15, 0
	v_lshl_or_b32 v1, s7, 5, v1
	v_cmp_gt_u32_e64 s[0:1], 32, v130
	v_readlane_b32 s10, v250, 2
	v_readlane_b32 s11, v250, 3
	v_readlane_b32 s12, v250, 4
	v_readlane_b32 s13, v250, 5
	s_and_saveexec_b64 s[8:9], s[0:1]
	s_cbranch_execz .LBB0_991
	v_lshl_add_u32 v131, v1, 4, 0
	ds_read_b128 v[132:135], v131
	v_lshl_add_u32 v136, s4, 8, v1
	v_ashrrev_i32_e32 v137, 31, v136
	v_lshl_add_u64 v[136:137], v[136:137], 4, s[2:3]
	s_ashr_i32 s7, s6, 31
	s_waitcnt lgkmcnt(0)
	v_mov_b32_e32 v138, v133
	v_mov_b32_e32 v139, v134
	v_mov_b32_e32 v133, v135
	v_pk_add_f32 v[132:133], v[138:139], v[132:133]
	v_lshl_add_u64 v[136:137], s[6:7], 2, v[136:137]
	v_pk_add_f32 v[132:133], v[132:133], v[132:133] op_sel:[0,1] op_sel_hi:[1,0]
	global_store_dword v[136:137], v132, off sc1

;     __device__ __forceinline__ void fused(f32x4 (&acc)[2][2][4][2], const Unit& u, int wr, int wc, int fr, int fq, PG8_LAS unsigned char* lds, int wid, int lane) const {
;     ...
;         asm volatile("s_waitcnt vmcnt(0) lgkmcnt(0)" ::: "memory"); __builtin_amdgcn_s_barrier(); asm volatile("" ::: "memory");
;         const int col0 = u.pn * BM + wc * 32 + 4 * fq;
; #pragma unroll
;         for (int ai = 0; ai < 2; ++ai)
; #pragma unroll
;             for (int m = 0; m < 4; ++m) { const int r = ai * HALF + wr * 64 + m * 16 + fr; const float rs = R[r]; const size_t off = (size_t)(u.pm * BM + r) * 1024 + col0;
; #pragma unroll
;                 for (int bj = 0; bj < 2; ++bj)
; #pragma unroll
;                     for (int n = 0; n < 2; ++n) { const int c = bj * HALF + n * 16; const f32x4 xv = *(const f32x4*)(xres + off + c); const f32x4 wv = *(const f32x4*)(w + col0 + c);
;                         *(f32x4*)(out + off + c) = xv + acc[ai][bj][m][n] * rs * wv; }
;                 if (m & 1) asm volatile("" ::: "memory"); }
.LBB0_1001:
	s_or_b64 exec, exec, s[4:5]
	s_lshl_b32 s0, s34, 5
	s_lshl_b32 s1, s6, 8
	s_or_b32 s0, s1, s0
	v_lshrrev_b32_e32 v0, 2, v0
	v_add_u32_e32 v132, s7, v146
	v_readlane_b32 s12, v250, 0
	v_and_or_b32 v130, v0, 12, s0
	v_ashrrev_i32_e32 v133, 31, v132
	v_readlane_b32 s13, v250, 1
	v_readlane_b32 s14, v250, 2
	v_readlane_b32 s15, v250, 3
	v_ashrrev_i32_e32 v131, 31, v130
	v_lshlrev_b64 v[0:1], 10, v[132:133]
	v_mov_b32_e32 v134, s14
	v_mov_b32_e32 v135, s15
	v_lshl_add_u64 v[0:1], v[0:1], 0, v[130:131]
	v_readlane_b32 s0, v250, 10
	s_waitcnt vmcnt(0) lgkmcnt(0)
	s_barrier
	v_readlane_b32 s1, v250, 11
	v_readlane_b32 s16, v250, 4
	v_readlane_b32 s17, v250, 5
	v_lshl_add_u32 v133, v146, 2, 0
	v_add_u32_e32 v133, 0x1000, v133
	ds_read2_b32 v[236:237], v133 offset0:0 offset1:16
	ds_read2_b32 v[238:239], v133 offset0:32 offset1:48
	ds_read2_b32 v[240:241], v133 offset0:128 offset1:144
	ds_read2_b32 v[242:243], v133 offset0:160 offset1:176
	s_waitcnt vmcnt(12) lgkmcnt(0)
	v_pk_mul_f32 v[126:127], v[126:127], v[236:237] op_sel_hi:[1,0]
	v_pk_mul_f32 v[128:129], v[128:129], v[236:237] op_sel_hi:[1,0]
	v_pk_mul_f32 v[122:123], v[122:123], v[236:237] op_sel_hi:[1,0]
	v_pk_mul_f32 v[124:125], v[124:125], v[236:237] op_sel_hi:[1,0]
	v_pk_mul_f32 v[118:119], v[118:119], v[236:237] op_sel_hi:[1,0]
	v_pk_mul_f32 v[120:121], v[120:121], v[236:237] op_sel_hi:[1,0]
	v_pk_mul_f32 v[110:111], v[110:111], v[236:237] op_sel_hi:[1,0]
	v_pk_mul_f32 v[112:113], v[112:113], v[236:237] op_sel_hi:[1,0]
	v_pk_fma_f32 v[126:127], v[126:127], v[148:149], v[164:165]
	v_pk_fma_f32 v[128:129], v[128:129], v[150:151], v[166:167]
	v_pk_fma_f32 v[122:123], v[122:123], v[152:153], v[168:169]
	v_pk_fma_f32 v[124:125], v[124:125], v[154:155], v[170:171]
	v_pk_fma_f32 v[118:119], v[118:119], v[156:157], v[172:173]
	v_pk_fma_f32 v[120:121], v[120:121], v[158:159], v[174:175]
	v_pk_fma_f32 v[110:111], v[110:111], v[160:161], v[176:177]
	v_pk_fma_f32 v[112:113], v[112:113], v[162:163], v[178:179]
	global_store_dwordx4 v228, v[126:129], s[16:17]
	global_store_dwordx4 v228, v[122:125], s[16:17] offset:64
	global_store_dwordx4 v228, v[118:121], s[16:17] offset:512
	global_store_dwordx4 v228, v[110:113], s[16:17] offset:576
	global_load_dwordx4 v[164:167], v232, s[0:1]
	global_load_dwordx4 v[168:171], v232, s[0:1] offset:64
	global_load_dwordx4 v[172:175], v232, s[0:1] offset:512
	global_load_dwordx4 v[176:179], v232, s[0:1] offset:576
	s_waitcnt vmcnt(16)
	v_pk_mul_f32 v[114:115], v[114:115], v[236:237] op_sel:[0,1] op_sel_hi:[1,1]
	v_pk_mul_f32 v[116:117], v[116:117], v[236:237] op_sel:[0,1] op_sel_hi:[1,1]
	v_pk_mul_f32 v[106:107], v[106:107], v[236:237] op_sel:[0,1] op_sel_hi:[1,1]
	v_pk_mul_f32 v[108:109], v[108:109], v[236:237] op_sel:[0,1] op_sel_hi:[1,1]
	v_pk_mul_f32 v[102:103], v[102:103], v[236:237] op_sel:[0,1] op_sel_hi:[1,1]
	v_pk_mul_f32 v[104:105], v[104:105], v[236:237] op_sel:[0,1] op_sel_hi:[1,1]
	v_pk_mul_f32 v[94:95], v[94:95], v[236:237] op_sel:[0,1] op_sel_hi:[1,1]
	v_pk_mul_f32 v[96:97], v[96:97], v[236:237] op_sel:[0,1] op_sel_hi:[1,1]
	v_pk_fma_f32 v[114:115], v[114:115], v[148:149], v[180:181]
	v_pk_fma_f32 v[116:117], v[116:117], v[150:151], v[182:183]
	v_pk_fma_f32 v[106:107], v[106:107], v[152:153], v[184:185]
	v_pk_fma_f32 v[108:109], v[108:109], v[154:155], v[186:187]
	v_pk_fma_f32 v[102:103], v[102:103], v[156:157], v[188:189]
	v_pk_fma_f32 v[104:105], v[104:105], v[158:159], v[190:191]
	v_pk_fma_f32 v[94:95], v[94:95], v[160:161], v[192:193]
	v_pk_fma_f32 v[96:97], v[96:97], v[162:163], v[194:195]
	global_store_dwordx4 v229, v[114:117], s[16:17]
	global_store_dwordx4 v229, v[106:109], s[16:17] offset:64
	global_store_dwordx4 v229, v[102:105], s[16:17] offset:512
	global_store_dwordx4 v229, v[94:97], s[16:17] offset:576
	global_load_dwordx4 v[180:183], v233, s[0:1]
	global_load_dwordx4 v[184:187], v233, s[0:1] offset:64
	global_load_dwordx4 v[188:191], v233, s[0:1] offset:512
	global_load_dwordx4 v[192:195], v233, s[0:1] offset:576
	s_waitcnt vmcnt(20)
	v_pk_mul_f32 v[98:99], v[98:99], v[238:239] op_sel_hi:[1,0]
	v_pk_mul_f32 v[100:101], v[100:101], v[238:239] op_sel_hi:[1,0]
	v_pk_mul_f32 v[90:91], v[90:91], v[238:239] op_sel_hi:[1,0]
	v_pk_mul_f32 v[92:93], v[92:93], v[238:239] op_sel_hi:[1,0]
	v_pk_mul_f32 v[86:87], v[86:87], v[238:239] op_sel_hi:[1,0]
	v_pk_mul_f32 v[88:89], v[88:89], v[238:239] op_sel_hi:[1,0]
	v_pk_mul_f32 v[78:79], v[78:79], v[238:239] op_sel_hi:[1,0]
	v_pk_mul_f32 v[80:81], v[80:81], v[238:239] op_sel_hi:[1,0]
	v_pk_fma_f32 v[98:99], v[98:99], v[148:149], v[196:197]
	v_pk_fma_f32 v[100:101], v[100:101], v[150:151], v[198:199]
	v_pk_fma_f32 v[90:91], v[90:91], v[152:153], v[200:201]
	v_pk_fma_f32 v[92:93], v[92:93], v[154:155], v[202:203]
	v_pk_fma_f32 v[86:87], v[86:87], v[156:157], v[204:205]
	v_pk_fma_f32 v[88:89], v[88:89], v[158:159], v[206:207]
	v_pk_fma_f32 v[78:79], v[78:79], v[160:161], v[208:209]
	v_pk_fma_f32 v[80:81], v[80:81], v[162:163], v[210:211]
	global_store_dwordx4 v230, v[98:101], s[16:17]
	global_store_dwordx4 v230, v[90:93], s[16:17] offset:64
	global_store_dwordx4 v230, v[86:89], s[16:17] offset:512
	global_store_dwordx4 v230, v[78:81], s[16:17] offset:576
	global_load_dwordx4 v[196:199], v234, s[0:1]
	global_load_dwordx4 v[200:203], v234, s[0:1] offset:64
	global_load_dwordx4 v[204:207], v234, s[0:1] offset:512
	global_load_dwordx4 v[208:211], v234, s[0:1] offset:576
	s_waitcnt vmcnt(24)
;     __device__ __forceinline__ void fused(f32x4 (&acc)[2][2][4][2], const Unit& u, int wr, int wc, int fr, int fq, PG8_LAS unsigned char* lds, int wid, int lane) const {
;     ...
; #pragma unroll
;         for (int ai = 0; ai < 2; ++ai)
; #pragma unroll
;             for (int m = 0; m < 4; ++m) { const int r = ai * HALF + wr * 64 + m * 16 + fr; const float rs = R[r]; const size_t off = (size_t)(u.pm * BM + r) * 1024 + col0;
; #pragma unroll
;                 for (int bj = 0; bj < 2; ++bj)
; #pragma unroll
;                     for (int n = 0; n < 2; ++n) { const int c = bj * HALF + n * 16; const f32x4 xv = *(const f32x4*)(xres + off + c); const f32x4 wv = *(const f32x4*)(w + col0 + c);
;                         *(f32x4*)(out + off + c) = xv + acc[ai][bj][m][n] * rs * wv; }
;                 if (m & 1) asm volatile("" ::: "memory"); }
	v_pk_mul_f32 v[82:83], v[82:83], v[238:239] op_sel:[0,1] op_sel_hi:[1,1]
	v_pk_mul_f32 v[84:85], v[84:85], v[238:239] op_sel:[0,1] op_sel_hi:[1,1]
	v_pk_mul_f32 v[74:75], v[74:75], v[238:239] op_sel:[0,1] op_sel_hi:[1,1]
	v_pk_mul_f32 v[76:77], v[76:77], v[238:239] op_sel:[0,1] op_sel_hi:[1,1]
	v_pk_mul_f32 v[70:71], v[70:71], v[238:239] op_sel:[0,1] op_sel_hi:[1,1]
	v_pk_mul_f32 v[72:73], v[72:73], v[238:239] op_sel:[0,1] op_sel_hi:[1,1]
	v_pk_mul_f32 v[66:67], v[66:67], v[238:239] op_sel:[0,1] op_sel_hi:[1,1]
	v_pk_mul_f32 v[68:69], v[68:69], v[238:239] op_sel:[0,1] op_sel_hi:[1,1]
	v_pk_fma_f32 v[82:83], v[82:83], v[148:149], v[212:213]
	v_pk_fma_f32 v[84:85], v[84:85], v[150:151], v[214:215]
	v_pk_fma_f32 v[74:75], v[74:75], v[152:153], v[216:217]
	v_pk_fma_f32 v[76:77], v[76:77], v[154:155], v[218:219]
	v_pk_fma_f32 v[70:71], v[70:71], v[156:157], v[220:221]
	v_pk_fma_f32 v[72:73], v[72:73], v[158:159], v[222:223]
	v_pk_fma_f32 v[66:67], v[66:67], v[160:161], v[224:225]
	v_pk_fma_f32 v[68:69], v[68:69], v[162:163], v[226:227]
	global_store_dwordx4 v231, v[82:85], s[16:17]
	global_store_dwordx4 v231, v[74:77], s[16:17] offset:64
	global_store_dwordx4 v231, v[70:73], s[16:17] offset:512
	global_store_dwordx4 v231, v[66:69], s[16:17] offset:576
	global_load_dwordx4 v[212:215], v235, s[0:1]
	global_load_dwordx4 v[216:219], v235, s[0:1] offset:64
	global_load_dwordx4 v[220:223], v235, s[0:1] offset:512
	global_load_dwordx4 v[224:227], v235, s[0:1] offset:576
	s_waitcnt vmcnt(24)
	v_pk_mul_f32 v[62:63], v[62:63], v[240:241] op_sel_hi:[1,0]
	v_pk_mul_f32 v[64:65], v[64:65], v[240:241] op_sel_hi:[1,0]
	v_pk_mul_f32 v[58:59], v[58:59], v[240:241] op_sel_hi:[1,0]
	v_pk_mul_f32 v[60:61], v[60:61], v[240:241] op_sel_hi:[1,0]
	v_pk_mul_f32 v[54:55], v[54:55], v[240:241] op_sel_hi:[1,0]
	v_pk_mul_f32 v[56:57], v[56:57], v[240:241] op_sel_hi:[1,0]
	v_pk_mul_f32 v[46:47], v[46:47], v[240:241] op_sel_hi:[1,0]
	v_pk_mul_f32 v[48:49], v[48:49], v[240:241] op_sel_hi:[1,0]
	v_pk_fma_f32 v[62:63], v[62:63], v[148:149], v[164:165]
	v_pk_fma_f32 v[64:65], v[64:65], v[150:151], v[166:167]
	v_pk_fma_f32 v[58:59], v[58:59], v[152:153], v[168:169]
	v_pk_fma_f32 v[60:61], v[60:61], v[154:155], v[170:171]
	v_pk_fma_f32 v[54:55], v[54:55], v[156:157], v[172:173]
	v_pk_fma_f32 v[56:57], v[56:57], v[158:159], v[174:175]
	v_pk_fma_f32 v[46:47], v[46:47], v[160:161], v[176:177]
	v_pk_fma_f32 v[48:49], v[48:49], v[162:163], v[178:179]
	global_store_dwordx4 v232, v[62:65], s[16:17]
	global_store_dwordx4 v232, v[58:61], s[16:17] offset:64
	global_store_dwordx4 v232, v[54:57], s[16:17] offset:512
	global_store_dwordx4 v232, v[46:49], s[16:17] offset:576
	s_waitcnt vmcnt(20)
	v_pk_mul_f32 v[50:51], v[50:51], v[240:241] op_sel:[0,1] op_sel_hi:[1,1]
	v_pk_mul_f32 v[52:53], v[52:53], v[240:241] op_sel:[0,1] op_sel_hi:[1,1]
	v_pk_mul_f32 v[42:43], v[42:43], v[240:241] op_sel:[0,1] op_sel_hi:[1,1]
	v_pk_mul_f32 v[44:45], v[44:45], v[240:241] op_sel:[0,1] op_sel_hi:[1,1]
	v_pk_mul_f32 v[38:39], v[38:39], v[240:241] op_sel:[0,1] op_sel_hi:[1,1]
	v_pk_mul_f32 v[40:41], v[40:41], v[240:241] op_sel:[0,1] op_sel_hi:[1,1]
	v_pk_mul_f32 v[30:31], v[30:31], v[240:241] op_sel:[0,1] op_sel_hi:[1,1]
	v_pk_mul_f32 v[32:33], v[32:33], v[240:241] op_sel:[0,1] op_sel_hi:[1,1]
	v_pk_fma_f32 v[50:51], v[50:51], v[148:149], v[180:181]
	v_pk_fma_f32 v[52:53], v[52:53], v[150:151], v[182:183]
	v_pk_fma_f32 v[42:43], v[42:43], v[152:153], v[184:185]
	v_pk_fma_f32 v[44:45], v[44:45], v[154:155], v[186:187]
	v_pk_fma_f32 v[38:39], v[38:39], v[156:157], v[188:189]
	v_pk_fma_f32 v[40:41], v[40:41], v[158:159], v[190:191]
	v_pk_fma_f32 v[30:31], v[30:31], v[160:161], v[192:193]
	v_pk_fma_f32 v[32:33], v[32:33], v[162:163], v[194:195]
	global_store_dwordx4 v233, v[50:53], s[16:17]
	global_store_dwordx4 v233, v[42:45], s[16:17] offset:64
	global_store_dwordx4 v233, v[38:41], s[16:17] offset:512
	global_store_dwordx4 v233, v[30:33], s[16:17] offset:576
	s_waitcnt vmcnt(16)
	v_pk_mul_f32 v[34:35], v[34:35], v[242:243] op_sel_hi:[1,0]
	v_pk_mul_f32 v[36:37], v[36:37], v[242:243] op_sel_hi:[1,0]
	v_pk_mul_f32 v[26:27], v[26:27], v[242:243] op_sel_hi:[1,0]
	v_pk_mul_f32 v[28:29], v[28:29], v[242:243] op_sel_hi:[1,0]
	v_pk_mul_f32 v[22:23], v[22:23], v[242:243] op_sel_hi:[1,0]
	v_pk_mul_f32 v[24:25], v[24:25], v[242:243] op_sel_hi:[1,0]
	v_pk_mul_f32 v[14:15], v[14:15], v[242:243] op_sel_hi:[1,0]
	v_pk_mul_f32 v[16:17], v[16:17], v[242:243] op_sel_hi:[1,0]
	v_pk_fma_f32 v[34:35], v[34:35], v[148:149], v[196:197]
	v_pk_fma_f32 v[36:37], v[36:37], v[150:151], v[198:199]
	v_pk_fma_f32 v[26:27], v[26:27], v[152:153], v[200:201]
	v_pk_fma_f32 v[28:29], v[28:29], v[154:155], v[202:203]
	v_pk_fma_f32 v[22:23], v[22:23], v[156:157], v[204:205]
	v_pk_fma_f32 v[24:25], v[24:25], v[158:159], v[206:207]
	v_pk_fma_f32 v[14:15], v[14:15], v[160:161], v[208:209]
	v_pk_fma_f32 v[16:17], v[16:17], v[162:163], v[210:211]
	global_store_dwordx4 v234, v[34:37], s[16:17]
	global_store_dwordx4 v234, v[26:29], s[16:17] offset:64
	global_store_dwordx4 v234, v[22:25], s[16:17] offset:512
	global_store_dwordx4 v234, v[14:17], s[16:17] offset:576
	s_waitcnt vmcnt(12)
	v_pk_mul_f32 v[18:19], v[18:19], v[242:243] op_sel:[0,1] op_sel_hi:[1,1]
	v_pk_mul_f32 v[20:21], v[20:21], v[242:243] op_sel:[0,1] op_sel_hi:[1,1]
	v_pk_mul_f32 v[10:11], v[10:11], v[242:243] op_sel:[0,1] op_sel_hi:[1,1]
	v_pk_mul_f32 v[12:13], v[12:13], v[242:243] op_sel:[0,1] op_sel_hi:[1,1]
	v_pk_mul_f32 v[6:7], v[6:7], v[242:243] op_sel:[0,1] op_sel_hi:[1,1]
	v_pk_mul_f32 v[8:9], v[8:9], v[242:243] op_sel:[0,1] op_sel_hi:[1,1]
	v_pk_mul_f32 v[2:3], v[2:3], v[242:243] op_sel:[0,1] op_sel_hi:[1,1]
	v_pk_mul_f32 v[4:5], v[4:5], v[242:243] op_sel:[0,1] op_sel_hi:[1,1]
	v_pk_fma_f32 v[18:19], v[18:19], v[148:149], v[212:213]
	v_pk_fma_f32 v[20:21], v[20:21], v[150:151], v[214:215]
	v_pk_fma_f32 v[10:11], v[10:11], v[152:153], v[216:217]
	v_pk_fma_f32 v[12:13], v[12:13], v[154:155], v[218:219]
	v_pk_fma_f32 v[6:7], v[6:7], v[156:157], v[220:221]
	v_pk_fma_f32 v[8:9], v[8:9], v[158:159], v[222:223]
	v_pk_fma_f32 v[2:3], v[2:3], v[160:161], v[224:225]
	v_pk_fma_f32 v[4:5], v[4:5], v[162:163], v[226:227]
	global_store_dwordx4 v235, v[18:21], s[16:17]
	global_store_dwordx4 v235, v[10:13], s[16:17] offset:64
	global_store_dwordx4 v235, v[6:9], s[16:17] offset:512
	global_store_dwordx4 v235, v[2:5], s[16:17] offset:576
